# v99 with the attention key-loop head aligned to a 64-byte fetch line
# baseline (speedup 1.0000x reference)
; #define LAS __attribute__((address_space(3)))
; #define DMAT(kt, so) do { const unsigned rb_ = (unsigned)ROWBASE(kt); _Pragma("unroll") for (int r = 0; r < 3; ++r) if (wid + 8 * r < 22) \
;         __builtin_amdgcn_global_load_lds((const unsigned*)(dsrc[r] + (size_t)rb_ * dmul[r]), (LAS unsigned*)(lds + (so) + dlds[r]), 16, 0, 0); } while (0)
; __device__ __forceinline__ void attn_unit2(LAS unsigned char* lds, const bf16_t* __restrict__ Q, const bf16_t* __restrict__ KN, const bf16_t* __restrict__ KPE, ...
;     ...
;         f32x16 sa0 = {}, sa1 = {}, sb0 = {}, sb1 = {};
;         const LAS unsigned char* ka = lds + sc + ka_off;
; #pragma unroll
;         for (int ds = 0; ds < 6; ++ds) {
;             const bf16x8 k0 = *(const LAS bf16x8*)(ka + ds * 32);
;             const bf16x8 k1 = *(const LAS bf16x8*)(ka + 32 * KROW + ds * 32);
;             sa0 = __builtin_amdgcn_mfma_f32_32x32x16_bf16(k0, qa[ds], sa0, 0, 0, 0);
;             sa1 = __builtin_amdgcn_mfma_f32_32x32x16_bf16(k1, qa[ds], sa1, 0, 0, 0);
;             sb0 = __builtin_amdgcn_mfma_f32_32x32x16_bf16(k0, qb[ds], sb0, 0, 0, 0);
;             sb1 = __builtin_amdgcn_mfma_f32_32x32x16_bf16(k1, qb[ds], sb1, 0, 0, 0);
;         }
;         __builtin_amdgcn_sched_barrier(0);
;         if (t + 2 < ntiles) DMAT(t + 2, snn);
;         u32x4 pa[4], pb[4];
.Lat_noprio:
	v_mov_b32_e32 v96, 0
	v_mov_b32_e32 v97, 0
	v_mov_b32_e32 v98, 0
	v_mov_b32_e32 v99, 0
	v_mov_b32_e32 v100, 0
	v_mov_b32_e32 v101, 0
	v_mov_b32_e32 v102, 0
	v_mov_b32_e32 v103, 0
	v_mov_b32_e32 v112, 0
	v_mov_b32_e32 v113, 0
	v_mov_b32_e32 v114, 0
	v_mov_b32_e32 v115, 0
	v_mov_b32_e32 v116, 0
	v_mov_b32_e32 v117, 0
	v_mov_b32_e32 v118, 0
	v_mov_b32_e32 v119, 0
	v_sub_u32_e32 v228, 1, v192
	v_mul_u32_u24_e32 v228, 0xffff, v228
	v_and_b32_e32 v240, 0x3f80, v228
	v_mov_b32_e32 v241, 0
	v_mov_b32_e32 v242, 0
	v_mov_b32_e32 v243, 0
	v_mov_b32_e32 v245, 0
	v_mov_b32_e32 v246, 0
	v_mov_b32_e32 v247, 0
	v_mov_b32_e32 v249, 0
	v_mov_b32_e32 v250, 0
	v_mov_b32_e32 v251, 0
	v_add3_u32 v224, s34, v183, v128
	ds_read_b128 v[212:215], v224 offset:0
	ds_read_b128 v[216:219], v224 offset:32
	ds_read_b128 v[220:223], v224 offset:64
	s_waitcnt lgkmcnt(2)
	v_mfma_f32_32x32x16_bf16 v[64:79], v[212:215], v[130:133], 0
	v_mfma_f32_32x32x16_bf16 v[80:95], v[212:215], v[138:141], 0
	ds_read_b128 v[212:215], v224 offset:96
	s_waitcnt lgkmcnt(2)
	v_mfma_f32_32x32x16_bf16 v[64:79], v[216:219], v[134:137], v[64:79]
	v_mfma_f32_32x32x16_bf16 v[80:95], v[216:219], v[142:145], v[80:95]
	ds_read_b128 v[216:219], v224 offset:128
	s_waitcnt lgkmcnt(2)
	v_mfma_f32_32x32x16_bf16 v[64:79], v[220:223], v[146:149], v[64:79]
	v_mfma_f32_32x32x16_bf16 v[80:95], v[220:223], v[154:157], v[80:95]
	ds_read_b128 v[220:223], v224 offset:160
	s_waitcnt lgkmcnt(2)
	v_mfma_f32_32x32x16_bf16 v[64:79], v[212:215], v[150:153], v[64:79]
	v_mfma_f32_32x32x16_bf16 v[80:95], v[212:215], v[158:161], v[80:95]
	s_waitcnt lgkmcnt(1)
	v_mfma_f32_32x32x16_bf16 v[64:79], v[216:219], v[162:165], v[64:79]
	v_mfma_f32_32x32x16_bf16 v[80:95], v[216:219], v[170:173], v[80:95]
	s_waitcnt lgkmcnt(0)
	v_mfma_f32_32x32x16_bf16 v[64:79], v[220:223], v[166:169], v[64:79]
	v_mfma_f32_32x32x16_bf16 v[80:95], v[220:223], v[174:177], v[80:95]
	s_nop 15
	s_nop 3
	v_max3_f32 v226, v64, v65, v66
	v_max3_f32 v227, v67, v68, v69
	v_max3_f32 v226, v226, v70, v71
	v_max3_f32 v227, v227, v72, v73
	v_max3_f32 v226, v226, v74, v75
	v_max3_f32 v227, v227, v76, v77
	v_max3_f32 v226, v226, v78, v79
	v_max_f32_e32 v226, v226, v227
	v_mov_b32_e32 v227, v226
	s_nop 1
	v_permlane32_swap_b32_e32 v226, v227
	v_max_f32_e32 v226, v226, v227
	v_cvt_pk_bf16_f32 v227, v226, v226
	v_and_b32_e32 v194, 0xffff0000, v227
	v_xor_b32_e32 v227, 0x80000000, v194
	v_lshrrev_b32_e32 v227, 16, v227
	v_and_b32_e32 v244, v228, v227
	v_max3_f32 v236, v80, v81, v82
	v_max3_f32 v237, v83, v84, v85
	v_max3_f32 v236, v236, v86, v87
	v_max3_f32 v237, v237, v88, v89
	v_max3_f32 v236, v236, v90, v91
	v_max3_f32 v237, v237, v92, v93
	v_max3_f32 v236, v236, v94, v95
	v_max_f32_e32 v236, v236, v237
	v_mov_b32_e32 v237, v236
	s_nop 1
	v_permlane32_swap_b32_e32 v236, v237
	v_max_f32_e32 v236, v236, v237
	v_cvt_pk_bf16_f32 v237, v236, v236
	v_and_b32_e32 v195, 0xffff0000, v237
	v_xor_b32_e32 v237, 0x80000000, v195
	v_lshrrev_b32_e32 v237, 16, v237
	v_and_b32_e32 v248, v228, v237
	s_nop 3
	v_mfma_f32_32x32x16_bf16 v[64:79], v[240:243], v[244:247], v[64:79]
	v_mfma_f32_32x32x16_bf16 v[80:95], v[240:243], v[248:251], v[80:95]
	v_add3_u32 v225, s34, v187, v128
	ds_read_b128 v[196:199], v225 offset:13376
	ds_read_b128 v[200:203], v225 offset:17984
	ds_read_b128 v[204:207], v225 offset:13408
	ds_read_b128 v[208:211], v225 offset:18016
	s_nop 7
	s_nop 3
	s_nop 0
	s_nop 0
	s_nop 0
	s_nop 0
	s_nop 0
	s_nop 0
	s_nop 0
	s_nop 0
	s_nop 0
	s_nop 0
